# prep item loop: redundant vmcnt(0) at the top of every item removed (it only waited for the previous item's store acks in front of the new loads)
# speedup vs baseline: 1.0051x; 1.0051x over previous
; DI void phase_prep(const Params& p, int l, int bid, int nblk, char* smem) {
;     ...
;   for (int it = bid; it < NB * 36 * 6; it += nblk) {
;     const int pass = it % 6, bt = it / 6;
;     const int b = bt / 36, pt = bt % 36, pos0 = pt * 64;
;     const int seg_lo = (pos0 < CTXL) ? 0 : CTXL, seg_hi = (pos0 < CTXL) ? CTXL : TPB;
;     const size_t rbase = (size_t)b * TPB;
;     const int pfirst = pos0 + pg * 8;
;     ...
;       const int col = (pass - 2) * 256 + cg8;
;       float w0[8], w1[8], w2[8], bb[8];
; #pragma unroll
;       for (int e = 0; e < 8; ++e) { w0[e] = sw[col + e]; w1[e] = sw[1024 + col + e]; w2[e] = sw[2048 + col + e]; bb[e] = sb[col + e]; }
;       uint4 raw[10];
; #pragma unroll
;       for (int k = 0; k < 10; ++k) {
;         const int pn = pfirst + k - 1;
;         raw[k] = (pn >= seg_lo && pn < seg_hi) ? *(const uint4*)&PXBC[(rbase + pn) * 1024 + col] : make_uint4(0u, 0u, 0u, 0u);
.LBB0_808:
	s_mul_hi_i32 s84, s13, 0x2aaaaaab
	s_lshr_b32 s0, s84, 31
	s_add_i32 s84, s84, s0
	s_mul_i32 s0, s84, -6
	s_add_i32 s64, s13, s0
	s_mul_hi_i32 s0, s13, 0x4bda12f7
	s_lshr_b32 s1, s0, 31
	s_ashr_i32 s45, s0, 6
	s_mul_hi_i32 s0, s84, 0x38e38e39
	s_add_i32 s45, s45, s1
	s_lshr_b32 s1, s0, 31
	s_ashr_i32 s0, s0, 3
	s_add_i32 s0, s0, s1
	s_mul_i32 s0, s0, 36
	s_sub_i32 s0, s84, s0
	s_lshl_b32 s44, s0, 6
	s_cmp_lt_i32 s0, 4
	s_cselect_b64 s[48:49], -1, 0
	s_and_b64 s[0:1], s[48:49], exec
	s_movk_i32 s0, 0x900
	s_cselect_b32 s85, 0, 0x100
	s_cselect_b32 s55, 0x100, s0
	s_mul_hi_i32 s47, s45, 0x900
	s_mul_i32 s46, s45, 0x900
	s_cmp_gt_i32 s64, 1
	v_add_u32_e32 v148, s44, v175
	s_cbranch_scc0 .LBB0_850
	s_mul_i32 s0, s84, 0xfffffa00
	s_add_i32 s0, s0, s86
	v_add_u32_e32 v172, s0, v171
	v_lshlrev_b64 v[0:1], 2, v[172:173]
	v_lshl_add_u64 v[4:5], s[40:41], 0, v[0:1]
	v_add_co_u32_e32 v10, vcc, 0x1000, v4
	s_mov_b64 s[0:1], 0x1000
	s_nop 0
	v_addc_co_u32_e32 v11, vcc, 0, v5, vcc
	v_lshl_add_u64 v[6:7], v[4:5], 0, s[0:1]
	v_lshl_add_u64 v[8:9], v[4:5], 0, s[24:25]
	v_lshl_add_u64 v[16:17], s[42:43], 0, v[0:1]
	global_load_dwordx4 v[0:3], v[4:5], off offset:16
	global_load_dwordx4 v[12:15], v[4:5], off
	v_add_co_u32_e32 v4, vcc, 0x2000, v4
	v_cmp_ge_i32_e64 s[0:1], s55, v148
	s_nop 0
	v_addc_co_u32_e32 v5, vcc, 0, v5, vcc
	global_load_dwordx4 v[28:31], v[10:11], off
	global_load_dwordx4 v[20:23], v[4:5], off
	global_load_dwordx4 v[24:27], v[6:7], off offset:16
	s_nop 0
	global_load_dwordx4 v[8:11], v[8:9], off offset:16
	s_nop 0
	global_load_dwordx4 v[4:7], v[16:17], off offset:16
	s_nop 0
	global_load_dwordx4 v[16:19], v[16:17], off
	v_cmp_lt_i32_e32 vcc, s85, v148
	v_lshl_add_u64 v[150:151], v[172:173], 1, s[60:61]
	s_and_b64 s[34:35], vcc, s[0:1]
	v_mov_b32_e32 v62, 0
	v_mov_b32_e32 v66, 0
	v_mov_b32_e32 v67, 0
	v_mov_b32_e32 v64, 0
	v_mov_b32_e32 v65, 0
	s_and_saveexec_b64 s[0:1], s[34:35]
	s_cbranch_execz .LBB0_811
	v_add_u32_e32 v32, -1, v148
	v_mov_b32_e32 v33, v173
	v_lshl_add_u64 v[32:33], s[46:47], 0, v[32:33]
	v_lshlrev_b64 v[32:33], 11, v[32:33]
	v_lshl_add_u64 v[32:33], v[150:151], 0, v[32:33]
	global_load_dwordx4 v[64:67], v[32:33], off

; template <bool SWAP, int MI, class AF, class BF, class EF>
; DI void gemm_tile(const AF& af, const BF& bfn, const EF& ef, int m0, int n0, int K, char* smem) {
;     ...
; #pragma unroll
;   for (int i = 0; i < MI; ++i)
; #pragma unroll
;     for (int j = 0; j < 2; ++j)
; #pragma unroll
;       for (int rg = 0; rg < 4; ++rg) {
;         const int m = SWAP ? (m0 + wm * (MI * 32) + i * 32 + l32) : (m0 + wm * (MI * 32) + i * 32 + rg * 8 + h * 4);
;         const int n = SWAP ? (n0 + wn * 64 + j * 32 + rg * 8 + h * 4) : (n0 + wn * 64 + j * 32 + l32);
;         ef(m, n, acc[i][j][rg * 4 + 0], acc[i][j][rg * 4 + 1], acc[i][j][rg * 4 + 2], acc[i][j][rg * 4 + 3]);
;       }
; DI void phase_outproj(const Params& p, int l, int bid, int nblk, char* smem) {
;     ...
;   auto ef = [=](int m, int n, float v0, float v1, float v2, float v3) {
;     const int b = m / TPB, pos = m % TPB;
;     const float4 ga = *(const float4*)&MOD[(size_t)(l * 17 + (pos < CTXL ? 16 : b)) * 6144 + 2048 + n];
;     const float4 xo = *(const float4*)(xrow_ptr(pp, l == 0, b, pos) + n);
;     const float4 o = {xo.x + ga.x * v0, xo.y + ga.y * v1, xo.z + ga.z * v2, xo.w + ga.w * v3};
;     *(float4*)(xrow_wptr(pp, b, pos) + n) = o;
.Lop_go:
	s_lshl_b32 s18, s35, 2
	s_add_u32 s48, s48, s18
	s_addc_u32 s49, s49, 0
	s_add_u32 s50, s50, s18
	s_addc_u32 s51, s51, 0
	s_mul_i32 s19, s19, 0x6000
	v_readlane_b32 s20, v253, 19
	v_readlane_b32 s21, v253, 20
	s_add_u32 s20, s20, s19
	s_addc_u32 s21, s21, 0
	s_add_u32 s20, s20, s18
	s_addc_u32 s21, s21, 0
	s_add_u32 s20, s20, 0x2000
	s_addc_u32 s21, s21, 0
	v_and_b32_e32 v128, 31, v218
	v_lshrrev_b32_e32 v129, 7, v218
	v_bfe_u32 v130, v218, 5, 1
	v_bfe_u32 v131, v218, 6, 1
	v_lshl_add_u32 v128, v129, 6, v128
	v_mul_u32_u24_e32 v128, 528, v128
	v_lshlrev_b32_e32 v131, 8, v131
	v_lshl_add_u32 v131, v130, 4, v131
	v_add_u32_e32 v128, v128, v131
	v_lshrrev_b32_e32 v129, 5, v218
	v_and_b32_e32 v130, 31, v218
	v_lshlrev_b32_e32 v132, 12, v129
	v_lshlrev_b32_e32 v133, 4, v130
	v_lshl_add_u32 v132, v130, 4, v132
	global_load_dwordx4 v[136:139], v133, s[20:21]
	global_load_dwordx4 v[64:67], v132, s[48:49]
	s_add_u32 s48, s48, 0x8000
	s_addc_u32 s49, s49, 0
	global_load_dwordx4 v[68:71], v132, s[48:49]
	s_add_u32 s48, s48, 0x8000
	s_addc_u32 s49, s49, 0
	global_load_dwordx4 v[72:75], v132, s[48:49]
	s_add_u32 s48, s48, 0x8000
	s_addc_u32 s49, s49, 0
	global_load_dwordx4 v[76:79], v132, s[48:49]
	s_add_u32 s48, s48, 0x8000
	s_addc_u32 s49, s49, 0
	global_load_dwordx4 v[80:83], v132, s[48:49]
	s_add_u32 s48, s48, 0x8000
	s_addc_u32 s49, s49, 0
	global_load_dwordx4 v[84:87], v132, s[48:49]
	s_add_u32 s48, s48, 0x8000
	s_addc_u32 s49, s49, 0
	global_load_dwordx4 v[88:91], v132, s[48:49]
	s_add_u32 s48, s48, 0x8000
	s_addc_u32 s49, s49, 0
	global_load_dwordx4 v[92:95], v132, s[48:49]
	s_add_u32 s48, s48, 0x8000
	s_addc_u32 s49, s49, 0
	global_load_dwordx4 v[96:99], v132, s[48:49]
	s_add_u32 s48, s48, 0x8000
	s_addc_u32 s49, s49, 0
	global_load_dwordx4 v[100:103], v132, s[48:49]
	s_add_u32 s48, s48, 0x8000
	s_addc_u32 s49, s49, 0
	global_load_dwordx4 v[104:107], v132, s[48:49]
	s_add_u32 s48, s48, 0x8000
	s_addc_u32 s49, s49, 0
	global_load_dwordx4 v[108:111], v132, s[48:49]
	s_add_u32 s48, s48, 0x8000
	s_addc_u32 s49, s49, 0
	global_load_dwordx4 v[112:115], v132, s[48:49]
	s_add_u32 s48, s48, 0x8000
	s_addc_u32 s49, s49, 0
	global_load_dwordx4 v[116:119], v132, s[48:49]
	s_add_u32 s48, s48, 0x8000
	s_addc_u32 s49, s49, 0
	global_load_dwordx4 v[120:123], v132, s[48:49]
	s_add_u32 s48, s48, 0x8000
	s_addc_u32 s49, s49, 0
	global_load_dwordx4 v[124:127], v132, s[48:49]
	ds_write_b128 v128, v[48:51] offset:0
	ds_write_b128 v128, v[52:55] offset:32
	ds_write_b128 v128, v[56:59] offset:64
	ds_write_b128 v128, v[60:63] offset:96
	ds_write_b128 v128, v[32:35] offset:128
	ds_write_b128 v128, v[36:39] offset:160
	ds_write_b128 v128, v[40:43] offset:192
	ds_write_b128 v128, v[44:47] offset:224
	ds_write_b128 v128, v[16:19] offset:16896
	ds_write_b128 v128, v[20:23] offset:16928
	ds_write_b128 v128, v[24:27] offset:16960
	ds_write_b128 v128, v[28:31] offset:16992
	ds_write_b128 v128, v[0:3] offset:17024
	ds_write_b128 v128, v[4:7] offset:17056
	ds_write_b128 v128, v[8:11] offset:17088
	ds_write_b128 v128, v[12:15] offset:17120
	v_mul_u32_u24_e32 v131, 528, v129
	v_lshl_add_u32 v131, v130, 4, v131
	s_waitcnt lgkmcnt(0)
	s_barrier
; DI void phase_outproj(const Params& p, int l, int bid, int nblk, char* smem) {
;     ...
;   auto ef = [=](int m, int n, float v0, float v1, float v2, float v3) {
;     const int b = m / TPB, pos = m % TPB;
;     const float4 ga = *(const float4*)&MOD[(size_t)(l * 17 + (pos < CTXL ? 16 : b)) * 6144 + 2048 + n];
;     const float4 xo = *(const float4*)(xrow_ptr(pp, l == 0, b, pos) + n);
;     const float4 o = {xo.x + ga.x * v0, xo.y + ga.y * v1, xo.z + ga.z * v2, xo.w + ga.w * v3};
;     *(float4*)(xrow_wptr(pp, b, pos) + n) = o;
;   };
;   const int ntile = (l == 1 ? NB * 16 : ROWS / 128) * 8;
;   const int vb = (nblk % 8 == 0) ? (bid & 7) * (nblk >> 3) + (bid >> 3) : bid;
;   for (int t = vb; t < ntile; t += nblk) {
;     const int mi = t >> 3, nt = t & 7;
;     const int mt = (l == 1) ? (mi >> 4) * 18 + 2 + (mi & 15) : mi;
;     gemm_tile<true, 2>(af, bfn, ef, mt * 128, nt * 128, 1024, smem);
;   }
	ds_read_b128 v[0:3], v131 offset:0
	ds_read_b128 v[4:7], v131 offset:4224
	ds_read_b128 v[8:11], v131 offset:8448
	ds_read_b128 v[12:15], v131 offset:12672
	ds_read_b128 v[16:19], v131 offset:16896
	ds_read_b128 v[20:23], v131 offset:21120
	ds_read_b128 v[24:27], v131 offset:25344
	ds_read_b128 v[28:31], v131 offset:29568
	ds_read_b128 v[32:35], v131 offset:33792
	ds_read_b128 v[36:39], v131 offset:38016
	ds_read_b128 v[40:43], v131 offset:42240
	ds_read_b128 v[44:47], v131 offset:46464
	ds_read_b128 v[48:51], v131 offset:50688
	ds_read_b128 v[52:55], v131 offset:54912
	ds_read_b128 v[56:59], v131 offset:59136
	ds_read_b128 v[60:63], v131 offset:63360
	s_waitcnt vmcnt(15) lgkmcnt(15)
	v_pk_fma_f32 v[0:1], v[136:137], v[0:1], v[64:65]
	v_pk_fma_f32 v[2:3], v[138:139], v[2:3], v[66:67]
	s_nop 0
	global_store_dwordx4 v132, v[0:3], s[50:51]
	s_add_u32 s50, s50, 0x8000
	s_addc_u32 s51, s51, 0
	s_waitcnt vmcnt(15) lgkmcnt(14)
	v_pk_fma_f32 v[4:5], v[136:137], v[4:5], v[68:69]
	v_pk_fma_f32 v[6:7], v[138:139], v[6:7], v[70:71]
	s_nop 0
	global_store_dwordx4 v132, v[4:7], s[50:51]
	s_add_u32 s50, s50, 0x8000
	s_addc_u32 s51, s51, 0
	s_waitcnt vmcnt(15) lgkmcnt(13)
	v_pk_fma_f32 v[8:9], v[136:137], v[8:9], v[72:73]
	v_pk_fma_f32 v[10:11], v[138:139], v[10:11], v[74:75]
	s_nop 0
	global_store_dwordx4 v132, v[8:11], s[50:51]
	s_add_u32 s50, s50, 0x8000
	s_addc_u32 s51, s51, 0
	s_waitcnt vmcnt(15) lgkmcnt(12)
	v_pk_fma_f32 v[12:13], v[136:137], v[12:13], v[76:77]
	v_pk_fma_f32 v[14:15], v[138:139], v[14:15], v[78:79]
	s_nop 0
	global_store_dwordx4 v132, v[12:15], s[50:51]
	s_add_u32 s50, s50, 0x8000
	s_addc_u32 s51, s51, 0
	s_waitcnt vmcnt(15) lgkmcnt(11)
	v_pk_fma_f32 v[16:17], v[136:137], v[16:17], v[80:81]
	v_pk_fma_f32 v[18:19], v[138:139], v[18:19], v[82:83]
	s_nop 0
	global_store_dwordx4 v132, v[16:19], s[50:51]
	s_add_u32 s50, s50, 0x8000
	s_addc_u32 s51, s51, 0
	s_waitcnt vmcnt(15) lgkmcnt(10)
	v_pk_fma_f32 v[20:21], v[136:137], v[20:21], v[84:85]
	v_pk_fma_f32 v[22:23], v[138:139], v[22:23], v[86:87]
	s_nop 0
	global_store_dwordx4 v132, v[20:23], s[50:51]
	s_add_u32 s50, s50, 0x8000
	s_addc_u32 s51, s51, 0
	s_waitcnt vmcnt(15) lgkmcnt(9)
	v_pk_fma_f32 v[24:25], v[136:137], v[24:25], v[88:89]
	v_pk_fma_f32 v[26:27], v[138:139], v[26:27], v[90:91]
	s_nop 0
	global_store_dwordx4 v132, v[24:27], s[50:51]
	s_add_u32 s50, s50, 0x8000
	s_addc_u32 s51, s51, 0
	s_waitcnt vmcnt(15) lgkmcnt(8)
	v_pk_fma_f32 v[28:29], v[136:137], v[28:29], v[92:93]
	v_pk_fma_f32 v[30:31], v[138:139], v[30:31], v[94:95]
	s_nop 0
	global_store_dwordx4 v132, v[28:31], s[50:51]
	s_add_u32 s50, s50, 0x8000
	s_addc_u32 s51, s51, 0
	s_waitcnt vmcnt(15) lgkmcnt(7)
	v_pk_fma_f32 v[32:33], v[136:137], v[32:33], v[96:97]
	v_pk_fma_f32 v[34:35], v[138:139], v[34:35], v[98:99]
	s_nop 0
	global_store_dwordx4 v132, v[32:35], s[50:51]
	s_add_u32 s50, s50, 0x8000
	s_addc_u32 s51, s51, 0
	s_waitcnt vmcnt(15) lgkmcnt(6)
	v_pk_fma_f32 v[36:37], v[136:137], v[36:37], v[100:101]
	v_pk_fma_f32 v[38:39], v[138:139], v[38:39], v[102:103]
	s_nop 0
	global_store_dwordx4 v132, v[36:39], s[50:51]
	s_add_u32 s50, s50, 0x8000
	s_addc_u32 s51, s51, 0
	s_waitcnt vmcnt(15) lgkmcnt(5)
	v_pk_fma_f32 v[40:41], v[136:137], v[40:41], v[104:105]
	v_pk_fma_f32 v[42:43], v[138:139], v[42:43], v[106:107]
	s_nop 0
	global_store_dwordx4 v132, v[40:43], s[50:51]
	s_add_u32 s50, s50, 0x8000
	s_addc_u32 s51, s51, 0
	s_waitcnt vmcnt(15) lgkmcnt(4)
	v_pk_fma_f32 v[44:45], v[136:137], v[44:45], v[108:109]
	v_pk_fma_f32 v[46:47], v[138:139], v[46:47], v[110:111]
	s_nop 0
	global_store_dwordx4 v132, v[44:47], s[50:51]
	s_add_u32 s50, s50, 0x8000
	s_addc_u32 s51, s51, 0
	s_waitcnt vmcnt(15) lgkmcnt(3)
	v_pk_fma_f32 v[48:49], v[136:137], v[48:49], v[112:113]
	v_pk_fma_f32 v[50:51], v[138:139], v[50:51], v[114:115]
	s_nop 0
	global_store_dwordx4 v132, v[48:51], s[50:51]
	s_add_u32 s50, s50, 0x8000
	s_addc_u32 s51, s51, 0
	s_waitcnt vmcnt(15) lgkmcnt(2)
	v_pk_fma_f32 v[52:53], v[136:137], v[52:53], v[116:117]
	v_pk_fma_f32 v[54:55], v[138:139], v[54:55], v[118:119]
	s_nop 0
	global_store_dwordx4 v132, v[52:55], s[50:51]
	s_add_u32 s50, s50, 0x8000
	s_addc_u32 s51, s51, 0
	s_waitcnt vmcnt(15) lgkmcnt(1)
	v_pk_fma_f32 v[56:57], v[136:137], v[56:57], v[120:121]
	v_pk_fma_f32 v[58:59], v[138:139], v[58:59], v[122:123]
	s_nop 0
	global_store_dwordx4 v132, v[56:59], s[50:51]
	s_add_u32 s50, s50, 0x8000
	s_addc_u32 s51, s51, 0
	s_waitcnt vmcnt(15) lgkmcnt(0)
	v_pk_fma_f32 v[60:61], v[136:137], v[60:61], v[124:125]
	v_pk_fma_f32 v[62:63], v[138:139], v[62:63], v[126:127]
	s_nop 0
	global_store_dwordx4 v132, v[60:63], s[50:51]
	s_barrier
	s_add_i32 s34, s34, s54
	s_cmp_lt_i32 s34, s13
	s_cbranch_scc1 .LBB0_1262
	v_readlane_b32 s18, v254, 10
	s_mov_b64 s[20:21], s[46:47]
	s_mov_b32 s24, s64
	v_readlane_b32 s19, v254, 11
